# attention-C: the 32 bias lookups per key row issued together into dead registers behind one wait (were chained through two temporaries, lgkmcnt(1) between each)
# baseline (speedup 1.0000x reference)
.LBB0_518:
	v_cmp_ge_i32_e32 vcc, s86, v134
	v_cmp_lt_u32_e64 s[0:1], s86, v135
	s_add_i32 s72, s90, -1
	s_and_b64 s[0:1], vcc, s[0:1]
	s_andn2_b64 vcc, exec, s[0:1]
	s_and_b32 s89, s72, 1
	s_cbranch_vccnz .LBB0_524
	s_lshl_b32 s0, s89, 13
	v_add_u32_e32 v40, s0, v136
	v_add_u32_e32 v41, v40, v137
	ds_read_b128 v[32:35], v41 offset:0
	ds_read_b128 v[36:39], v41 offset:0x1000
	v_add_u32_e32 v41, v40, v138
	ds_read_b128 v[88:91], v41 offset:0
	ds_read_b128 v[92:95], v41 offset:0x1000
	v_add_u32_e32 v41, v40, v139
	ds_read_b128 v[96:99], v41 offset:0
	ds_read_b128 v[100:103], v41 offset:0x1000
	v_add_u32_e32 v40, v40, v140
	ds_read_b128 v[104:107], v40 offset:0
	ds_read_b128 v[108:111], v40 offset:0x1000
	s_waitcnt lgkmcnt(0)
	v_mfma_f32_32x32x16_bf16 v[48:63], v[32:35], v[64:67], 0
	v_mfma_f32_32x32x16_bf16 v[32:47], v[36:39], v[64:67], 0
	v_mfma_f32_32x32x16_bf16 v[48:63], v[88:91], v[68:71], v[48:63]
	v_mfma_f32_32x32x16_bf16 v[32:47], v[92:95], v[68:71], v[32:47]
	v_mfma_f32_32x32x16_bf16 v[48:63], v[96:99], v[72:75], v[48:63]
	v_mfma_f32_32x32x16_bf16 v[32:47], v[100:103], v[72:75], v[32:47]
	v_mfma_f32_32x32x16_bf16 v[48:63], v[104:107], v[80:83], v[48:63]
	v_mfma_f32_32x32x16_bf16 v[32:47], v[108:111], v[80:83], v[32:47]
	v_add_u32_e32 v177, s0, v141
	ds_read_b64_tr_b16 v[116:117], v177 offset:0
	ds_read_b64_tr_b16 v[118:119], v177 offset:0x400
	ds_read_b64_tr_b16 v[104:105], v177 offset:0x800
	ds_read_b64_tr_b16 v[106:107], v177 offset:0xc00
	ds_read_b64_tr_b16 v[96:97], v177 offset:0x1000
	ds_read_b64_tr_b16 v[98:99], v177 offset:0x1400
	ds_read_b64_tr_b16 v[92:93], v177 offset:0x1800
	ds_read_b64_tr_b16 v[94:95], v177 offset:0x1c00
	ds_read_b64_tr_b16 v[112:113], v177 offset:0x200
	ds_read_b64_tr_b16 v[114:115], v177 offset:0x600
	ds_read_b64_tr_b16 v[108:109], v177 offset:0xa00
	ds_read_b64_tr_b16 v[110:111], v177 offset:0xe00
	ds_read_b64_tr_b16 v[100:101], v177 offset:0x1200
	ds_read_b64_tr_b16 v[102:103], v177 offset:0x1600
	ds_read_b64_tr_b16 v[88:89], v177 offset:0x1a00
	ds_read_b64_tr_b16 v[90:91], v177 offset:0x1e00
	v_add_u32_e32 v204, s88, v173
	ds_read_b32 v204, v204
	v_add_u32_e32 v205, s88, v172
	ds_read_b32 v205, v205
	v_add_u32_e32 v206, s88, v171
	ds_read_b32 v206, v206
	v_add_u32_e32 v207, s88, v170
	ds_read_b32 v207, v207
	v_add_u32_e32 v208, s88, v169
	ds_read_b32 v208, v208
	v_add_u32_e32 v209, s88, v168
	ds_read_b32 v209, v209
	v_add_u32_e32 v210, s88, v167
	ds_read_b32 v210, v210
	v_add_u32_e32 v211, s88, v166
	ds_read_b32 v211, v211
	v_add_u32_e32 v212, s88, v165
	ds_read_b32 v212, v212
	v_add_u32_e32 v213, s88, v164
	ds_read_b32 v213, v213
	v_add_u32_e32 v214, s88, v163
	ds_read_b32 v214, v214
	v_add_u32_e32 v215, s88, v162
	ds_read_b32 v215, v215
	v_add_u32_e32 v216, s88, v161
	ds_read_b32 v216, v216
	v_add_u32_e32 v217, s88, v160
	ds_read_b32 v217, v217
	v_add_u32_e32 v236, s88, v159
	ds_read_b32 v236, v236
	v_add_u32_e32 v237, s88, v158
	ds_read_b32 v237, v237
	v_add_u32_e32 v238, s88, v157
	ds_read_b32 v238, v238
	v_add_u32_e32 v239, s88, v156
	ds_read_b32 v239, v239
	v_add_u32_e32 v240, s88, v155
	ds_read_b32 v240, v240
	v_add_u32_e32 v241, s88, v154
	ds_read_b32 v241, v241
	v_add_u32_e32 v242, s88, v153
	ds_read_b32 v242, v242
	v_add_u32_e32 v243, s88, v152
	ds_read_b32 v243, v243
	v_add_u32_e32 v244, s88, v151
	ds_read_b32 v244, v244
	v_add_u32_e32 v245, s88, v150
	ds_read_b32 v245, v245
	v_add_u32_e32 v246, s88, v149
	ds_read_b32 v246, v246
	v_add_u32_e32 v247, s88, v148
	ds_read_b32 v247, v247
	v_add_u32_e32 v248, s88, v147
	ds_read_b32 v248, v248
	v_add_u32_e32 v249, s88, v146
	ds_read_b32 v249, v249
	v_add_u32_e32 v250, s88, v145
	ds_read_b32 v250, v250
	v_add_u32_e32 v251, s88, v144
	ds_read_b32 v251, v251
	v_add_u32_e32 v192, s88, v143
	ds_read_b32 v192, v192
	v_add_u32_e32 v193, s88, v142
	ds_read_b32 v193, v193
	s_waitcnt lgkmcnt(0)
	v_add_f32_e32 v48, v48, v204
	v_add_f32_e32 v32, v32, v205
	v_add_f32_e32 v49, v49, v206
	v_add_f32_e32 v33, v33, v207
	v_add_f32_e32 v50, v50, v208
	v_add_f32_e32 v34, v34, v209
	v_add_f32_e32 v51, v51, v210
	v_add_f32_e32 v35, v35, v211
	v_add_f32_e32 v52, v52, v212
	v_add_f32_e32 v36, v36, v213
	v_add_f32_e32 v53, v53, v214
	v_add_f32_e32 v37, v37, v215
	v_add_f32_e32 v54, v54, v216
	v_add_f32_e32 v38, v38, v217
	v_add_f32_e32 v55, v55, v236
	v_add_f32_e32 v39, v39, v237
	v_add_f32_e32 v56, v56, v238
	v_add_f32_e32 v40, v40, v239
	v_add_f32_e32 v57, v57, v240
	v_add_f32_e32 v41, v41, v241
	v_add_f32_e32 v58, v58, v242
	v_add_f32_e32 v42, v42, v243
	v_add_f32_e32 v59, v59, v244
	v_add_f32_e32 v43, v43, v245
	v_add_f32_e32 v60, v60, v246
	v_add_f32_e32 v44, v44, v247
	v_add_f32_e32 v61, v61, v248
	v_add_f32_e32 v45, v45, v249
	v_add_f32_e32 v62, v62, v250
	v_add_f32_e32 v46, v46, v251
	v_add_f32_e32 v63, v63, v192
	v_add_f32_e32 v47, v47, v193
	v_cndmask_b32_e64 v48, v48, v232, s[6:7]
	v_cndmask_b32_e64 v49, v49, v232, s[10:11]
	v_cndmask_b32_e64 v50, v50, v232, s[14:15]
	v_cndmask_b32_e64 v51, v51, v232, s[18:19]
	v_cndmask_b32_e64 v52, v52, v232, s[22:23]
	v_cndmask_b32_e64 v53, v53, v232, s[26:27]
	v_cndmask_b32_e64 v54, v54, v232, s[30:31]
	v_cndmask_b32_e64 v55, v55, v232, s[36:37]
	v_cndmask_b32_e64 v56, v232, v56, s[40:41]
	v_cndmask_b32_e64 v57, v232, v57, s[44:45]
	v_cndmask_b32_e64 v58, v232, v58, s[48:49]
	v_cndmask_b32_e64 v59, v232, v59, s[52:53]
	v_cndmask_b32_e64 v60, v232, v60, s[56:57]
	v_cndmask_b32_e64 v61, v232, v61, s[60:61]
	v_cndmask_b32_e64 v62, v232, v62, s[64:65]
	v_max_f32_e32 v177, v48, v49
	v_max3_f32 v177, v177, v50, v51
	v_max3_f32 v177, v177, v52, v53
	v_max3_f32 v177, v177, v54, v55
	v_max3_f32 v177, v177, v56, v57
	v_max3_f32 v177, v177, v58, v59
	v_cndmask_b32_e64 v63, v232, v63, s[68:69]
	v_max3_f32 v177, v177, v60, v61
	v_cndmask_b32_e64 v32, v232, v32, s[8:9]
	v_cndmask_b32_e64 v33, v232, v33, s[12:13]
	v_max3_f32 v177, v177, v62, v63
	v_cndmask_b32_e64 v34, v232, v34, s[16:17]
	v_cndmask_b32_e64 v35, v232, v35, s[20:21]
	v_max3_f32 v177, v177, v32, v33
	v_cndmask_b32_e64 v36, v232, v36, s[24:25]
	v_cndmask_b32_e64 v37, v232, v37, s[28:29]
	v_max3_f32 v177, v177, v34, v35
	v_cndmask_b32_e64 v38, v232, v38, s[34:35]
	v_cndmask_b32_e64 v39, v232, v39, s[38:39]
	v_max3_f32 v177, v177, v36, v37
	v_cndmask_b32_e64 v40, v232, v40, s[42:43]
	v_cndmask_b32_e64 v41, v232, v41, s[46:47]
	v_max3_f32 v177, v177, v38, v39
	v_cndmask_b32_e64 v42, v232, v42, s[50:51]
	v_cndmask_b32_e64 v43, v232, v43, s[54:55]
	v_max3_f32 v177, v177, v40, v41
	v_cndmask_b32_e64 v44, v232, v44, s[58:59]
	v_cndmask_b32_e64 v45, v232, v45, s[62:63]
	v_max3_f32 v177, v177, v42, v43
	v_cndmask_b32_e64 v46, v232, v46, s[66:67]
	v_cndmask_b32_e64 v47, v232, v47, s[70:71]
	v_max3_f32 v177, v177, v44, v45
	v_max3_f32 v177, v177, v46, v47
	v_mov_b32_e32 v178, v177
	s_nop 1
	v_permlane32_swap_b32_e32 v177, v178
	v_max_f32_e32 v178, v178, v178
	v_max_f32_e32 v177, v177, v177
	v_max_f32_e32 v177, v177, v178
	v_sub_f32_e32 v178, v177, v175
	v_cmp_ge_f32_e32 vcc, s85, v178
	s_cmp_eq_u64 vcc, exec
	v_max_f32_e32 v178, v175, v175
	s_cselect_b64 vcc, -1, 0
	v_max_f32_e32 v177, v178, v177
	v_sub_f32_e32 v178, v175, v177
	v_cndmask_b32_e32 v175, v177, v175, vcc
	v_mul_f32_e32 v177, 0xbe38aa3b, v175
	v_fmamk_f32 v48, v48, 0x3e38aa3b, v177
	v_exp_f32_e32 v179, v48
	v_fmamk_f32 v49, v49, 0x3e38aa3b, v177
	v_exp_f32_e32 v180, v49
	v_fmamk_f32 v49, v50, 0x3e38aa3b, v177
	v_exp_f32_e32 v181, v49
	v_fmamk_f32 v49, v51, 0x3e38aa3b, v177
	v_exp_f32_e32 v51, v49
	v_fmamk_f32 v49, v52, 0x3e38aa3b, v177
	v_add_f32_e32 v48, 0, v179
	v_exp_f32_e32 v52, v49
	v_fmamk_f32 v49, v53, 0x3e38aa3b, v177
	v_add_f32_e32 v48, v180, v48
	v_exp_f32_e32 v53, v49
	v_fmamk_f32 v49, v54, 0x3e38aa3b, v177
	v_add_f32_e32 v48, v181, v48
	v_exp_f32_e32 v54, v49
	v_fmamk_f32 v49, v55, 0x3e38aa3b, v177
	v_add_f32_e32 v48, v51, v48
	v_exp_f32_e32 v55, v49
	v_fmamk_f32 v49, v56, 0x3e38aa3b, v177
	v_add_f32_e32 v48, v52, v48
	v_exp_f32_e32 v56, v49
	v_fmamk_f32 v49, v57, 0x3e38aa3b, v177
	v_add_f32_e32 v48, v53, v48
	v_exp_f32_e32 v57, v49
	v_fmamk_f32 v49, v58, 0x3e38aa3b, v177
	v_add_f32_e32 v48, v54, v48
	v_exp_f32_e32 v58, v49
	v_fmamk_f32 v49, v59, 0x3e38aa3b, v177
	v_add_f32_e32 v48, v55, v48
	v_exp_f32_e32 v59, v49
	v_fmamk_f32 v49, v60, 0x3e38aa3b, v177
	v_add_f32_e32 v48, v56, v48
	v_exp_f32_e32 v60, v49
	v_fmamk_f32 v49, v61, 0x3e38aa3b, v177
	v_add_f32_e32 v48, v57, v48
	v_exp_f32_e32 v61, v49
	v_fmamk_f32 v49, v62, 0x3e38aa3b, v177
	v_add_f32_e32 v48, v58, v48
	v_exp_f32_e32 v62, v49
	v_fmamk_f32 v49, v63, 0x3e38aa3b, v177
	v_add_f32_e32 v48, v59, v48
	v_exp_f32_e32 v63, v49
	v_fmamk_f32 v32, v32, 0x3e38aa3b, v177
	v_add_f32_e32 v48, v60, v48
	v_exp_f32_e32 v32, v32
	v_fmamk_f32 v33, v33, 0x3e38aa3b, v177
	v_add_f32_e32 v48, v61, v48
	v_exp_f32_e32 v33, v33
	v_fmamk_f32 v34, v34, 0x3e38aa3b, v177
	v_add_f32_e32 v48, v62, v48
	v_exp_f32_e32 v34, v34
	v_fmamk_f32 v35, v35, 0x3e38aa3b, v177
	v_add_f32_e32 v48, v63, v48
	v_exp_f32_e32 v35, v35
	v_fmamk_f32 v36, v36, 0x3e38aa3b, v177
	v_add_f32_e32 v48, v32, v48
	v_exp_f32_e32 v182, v36
	v_fmamk_f32 v37, v37, 0x3e38aa3b, v177
	v_add_f32_e32 v48, v33, v48
	v_exp_f32_e32 v183, v37
	v_fmamk_f32 v37, v38, 0x3e38aa3b, v177
	v_add_f32_e32 v48, v34, v48
	v_exp_f32_e32 v184, v37
	v_fmamk_f32 v37, v39, 0x3e38aa3b, v177
	v_add_f32_e32 v48, v35, v48
	v_exp_f32_e32 v39, v37
	v_fmamk_f32 v37, v40, 0x3e38aa3b, v177
	v_add_f32_e32 v36, v182, v48
	v_exp_f32_e32 v185, v37
	v_fmamk_f32 v37, v41, 0x3e38aa3b, v177
	v_add_f32_e32 v36, v183, v36
	v_exp_f32_e32 v186, v37
	v_fmamk_f32 v37, v42, 0x3e38aa3b, v177
	v_add_f32_e32 v36, v184, v36
	v_exp_f32_e32 v187, v37
	v_fmamk_f32 v37, v43, 0x3e38aa3b, v177
	v_add_f32_e32 v36, v39, v36
	v_exp_f32_e32 v188, v37
	v_fmamk_f32 v37, v44, 0x3e38aa3b, v177
	v_add_f32_e32 v36, v185, v36
	v_exp_f32_e32 v189, v37
	v_fmamk_f32 v37, v45, 0x3e38aa3b, v177
	v_add_f32_e32 v36, v186, v36
	v_exp_f32_e32 v190, v37
	v_fmamk_f32 v37, v46, 0x3e38aa3b, v177
	v_add_f32_e32 v36, v187, v36
	v_exp_f32_e32 v191, v37
	v_fmac_f32_e32 v177, 0x3e38aa3b, v47
	v_mul_f32_e32 v178, 0x3e38aa3b, v178
	v_add_f32_e32 v36, v188, v36
	v_exp_f32_e32 v177, v177
	v_exp_f32_e32 v178, v178
	v_add_f32_e32 v36, v189, v36
	v_add_f32_e32 v36, v190, v36
	v_add_f32_e32 v36, v191, v36
	v_add_f32_e32 v49, v177, v36
	v_cndmask_b32_e64 v48, v178, 1.0, vcc
	v_mov_b32_e32 v50, v49
	v_cvt_pk_bf16_f32 v44, v179, v180
	v_cvt_pk_bf16_f32 v45, v181, v51
	v_cvt_pk_bf16_f32 v46, v52, v53
	v_cvt_pk_bf16_f32 v47, v54, v55
	v_cvt_pk_bf16_f32 v40, v56, v57
	v_cvt_pk_bf16_f32 v41, v58, v59
	v_cvt_pk_bf16_f32 v42, v60, v61
	v_cvt_pk_bf16_f32 v43, v62, v63
	v_cvt_pk_bf16_f32 v36, v32, v33
	v_cvt_pk_bf16_f32 v37, v34, v35
	v_cvt_pk_bf16_f32 v38, v182, v183
	v_cvt_pk_bf16_f32 v39, v184, v39
	v_cvt_pk_bf16_f32 v32, v185, v186
	v_cvt_pk_bf16_f32 v33, v187, v188
	v_cvt_pk_bf16_f32 v34, v189, v190
	v_cvt_pk_bf16_f32 v35, v191, v177
	s_nop 1
	v_permlane32_swap_b32_e32 v49, v50
	v_permlane32_swap_b32_e32 v44, v46
	v_permlane32_swap_b32_e32 v45, v47
	v_permlane32_swap_b32_e32 v40, v42
	v_permlane32_swap_b32_e32 v41, v43
	v_permlane32_swap_b32_e32 v36, v38
	v_permlane32_swap_b32_e32 v37, v39
	v_permlane32_swap_b32_e32 v32, v34
	v_permlane32_swap_b32_e32 v33, v35
	v_cmp_gt_f32_e32 vcc, 1.0, v48
	s_cbranch_vccz .LBB0_523
	s_and_saveexec_b64 s[0:1], s[4:5]
	ds_write_b32 v131, v48 offset:128
	s_or_b64 exec, exec, s[0:1]
	s_waitcnt lgkmcnt(0)
	v_add_u32_e32 v51, s79, v194
	ds_read_b128 v[52:55], v51 offset:224
	ds_read_b128 v[56:59], v51 offset:192
	ds_read_b128 v[60:63], v51 offset:160
	ds_read_b128 v[178:181], v51 offset:128
	s_waitcnt lgkmcnt(3)
	v_pk_mul_f32 v[12:13], v[12:13], v[52:53]
	s_waitcnt lgkmcnt(2)
	v_pk_mul_f32 v[8:9], v[8:9], v[56:57]
	s_waitcnt lgkmcnt(1)
	v_pk_mul_f32 v[4:5], v[4:5], v[60:61]
	s_waitcnt lgkmcnt(0)
	v_pk_mul_f32 v[0:1], v[0:1], v[178:179]
	v_pk_mul_f32 v[28:29], v[28:29], v[52:53]
	v_pk_mul_f32 v[24:25], v[24:25], v[56:57]
	v_pk_mul_f32 v[20:21], v[20:21], v[60:61]
	v_pk_mul_f32 v[14:15], v[14:15], v[54:55]
	v_pk_mul_f32 v[10:11], v[10:11], v[58:59]
	v_pk_mul_f32 v[6:7], v[6:7], v[62:63]
	v_pk_mul_f32 v[2:3], v[2:3], v[180:181]
	v_pk_mul_f32 v[30:31], v[30:31], v[54:55]
	v_pk_mul_f32 v[26:27], v[26:27], v[58:59]
	v_pk_mul_f32 v[22:23], v[22:23], v[62:63]
	v_pk_mul_f32 v[18:19], v[18:19], v[180:181]
	v_pk_mul_f32 v[16:17], v[16:17], v[178:179]
